# recurrence fix-up phase: chunk-carry prefix loop software-pipelined (next 16 carry loads in flight while the current 8-chunk fma chain runs)
# speedup vs baseline: 1.0143x; 1.0143x over previous
;   DI bf16_t* h() const { return (bf16_t*)(ws + OFF_H); }
; DI void phase_scan_fix(const Params& p) {
;     ...
;     for (; cc + 8 <= c; cc += 8) {
;       f32x4 a[8], u[8];
; #pragma unroll
;       for (int j = 0; j < 8; ++j) { a[j] = *(const f32x4*)(cA + (size_t)(cc + j) * 1024); u[j] = *(const f32x4*)(cH + (size_t)(cc + j) * 1024); }
; #pragma unroll
;       for (int j = 0; j < 8; ++j) h = a[j] * h + u[j];
;     }
.LBB0_679:
	v_lshlrev_b32_e32 v1, 2, v97
	v_ashrrev_i32_e32 v6, 15, v96
	v_mov_b32_e32 v2, v0
	v_mov_b32_e32 v3, v0
	v_and_b32_e32 v70, 0xff0, v1
	v_bfe_u32 v14, v96, 8, 7
	v_ashrrev_i32_e32 v7, 31, v6
	v_mov_b32_e32 v1, v0
	v_mov_b64_e32 v[4:5], v[2:3]
	v_lshlrev_b64 v[8:9], 19, v[6:7]
	v_cmp_lt_u32_e32 vcc, 7, v14
	v_mov_b32_e32 v12, v71
	v_mov_b64_e32 v[2:3], v[0:1]
	s_and_saveexec_b64 s[2:3], vcc
	s_cbranch_execz .LBB0_683
	v_lshl_add_u64 v[2:3], v[8:9], 0, v[70:71]
	v_lshl_add_u64 v[10:11], s[4:5], 0, v[2:3]
	v_mov_b32_e32 v2, 0
	s_mov_b32 s33, 0
	s_mov_b64 s[16:17], 0
	v_mov_b32_e32 v3, v2
	v_mov_b32_e32 v4, v2
	v_mov_b32_e32 v5, v2
	v_add_co_u32_e32 v12, vcc, 0xffdf9000, v10
	global_load_dwordx4 v[100:103], v[10:11], off offset:-4096
	global_load_dwordx4 v[104:107], v[10:11], off
	v_addc_co_u32_e32 v13, vcc, -1, v11, vcc
	v_add_co_u32_e32 v112, vcc, 0xffff9000, v10
	s_nop 0
	s_nop 0
	v_addc_co_u32_e32 v113, vcc, -1, v11, vcc
	v_add_co_u32_e32 v116, vcc, 0xffdfa000, v10
	global_load_dwordx4 v[108:111], v[12:13], off
	s_nop 0
	global_load_dwordx4 v[112:115], v[112:113], off
	v_addc_co_u32_e32 v117, vcc, -1, v11, vcc
	v_add_co_u32_e32 v12, vcc, 0xffffa000, v10
	s_nop 0
	s_nop 0
	v_addc_co_u32_e32 v13, vcc, -1, v11, vcc
	v_add_co_u32_e32 v124, vcc, 0xffdfb000, v10
	global_load_dwordx4 v[116:119], v[116:117], off
	s_nop 0
	global_load_dwordx4 v[120:123], v[12:13], off
	v_addc_co_u32_e32 v125, vcc, -1, v11, vcc
	v_add_co_u32_e32 v12, vcc, 0xffffb000, v10
	s_nop 0
	s_nop 0
	v_addc_co_u32_e32 v13, vcc, -1, v11, vcc
	v_add_co_u32_e32 v132, vcc, 0xffdfc000, v10
	global_load_dwordx4 v[124:127], v[124:125], off
	s_nop 0
	global_load_dwordx4 v[128:131], v[12:13], off
	v_addc_co_u32_e32 v133, vcc, -1, v11, vcc
	v_add_co_u32_e32 v12, vcc, 0xffffc000, v10
	s_nop 0
	s_nop 0
	v_addc_co_u32_e32 v13, vcc, -1, v11, vcc
	v_add_co_u32_e32 v140, vcc, 0xffdfd000, v10
	global_load_dwordx4 v[132:135], v[132:133], off
	s_nop 0
	global_load_dwordx4 v[136:139], v[12:13], off
	v_addc_co_u32_e32 v141, vcc, -1, v11, vcc
	v_add_co_u32_e32 v12, vcc, 0xffffd000, v10
	s_nop 0
	s_nop 0
	v_addc_co_u32_e32 v13, vcc, -1, v11, vcc
	v_add_co_u32_e32 v148, vcc, 0xffdfe000, v10
	global_load_dwordx4 v[140:143], v[140:141], off
	s_nop 0
	global_load_dwordx4 v[144:147], v[12:13], off
	v_addc_co_u32_e32 v149, vcc, -1, v11, vcc
	v_add_co_u32_e32 v12, vcc, 0xffffe000, v10
	s_nop 0
	s_nop 0
	v_addc_co_u32_e32 v13, vcc, -1, v11, vcc
	v_add_co_u32_e32 v68, vcc, 0xffdff000, v10
	global_load_dwordx4 v[148:151], v[148:149], off
	s_nop 0
	global_load_dwordx4 v[156:159], v[12:13], off
	v_addc_co_u32_e32 v69, vcc, -1, v11, vcc
	v_add_co_u32_e32 v12, vcc, 0xffe00000, v10
	global_load_dwordx4 v[160:163], v[68:69], off
	s_nop 0
	v_addc_co_u32_e32 v13, vcc, -1, v11, vcc
	global_load_dwordx4 v[164:167], v[12:13], off
;   DI bf16_t* h() const { return (bf16_t*)(ws + OFF_H); }
; DI void phase_scan_fix(const Params& p) {
;     ...
;     for (; cc + 8 <= c; cc += 8) {
;       f32x4 a[8], u[8];
; #pragma unroll
;       for (int j = 0; j < 8; ++j) { a[j] = *(const f32x4*)(cA + (size_t)(cc + j) * 1024); u[j] = *(const f32x4*)(cH + (size_t)(cc + j) * 1024); }
; #pragma unroll
;       for (int j = 0; j < 8; ++j) h = a[j] * h + u[j];
;     }
.LBB0_681:
	s_waitcnt vmcnt(0)
	v_mov_b64_e32 v[16:17], v[100:101]
	v_mov_b64_e32 v[18:19], v[102:103]
	v_mov_b64_e32 v[20:21], v[104:105]
	v_mov_b64_e32 v[22:23], v[106:107]
	v_mov_b64_e32 v[24:25], v[108:109]
	v_mov_b64_e32 v[26:27], v[110:111]
	v_mov_b64_e32 v[28:29], v[112:113]
	v_mov_b64_e32 v[30:31], v[114:115]
	v_mov_b64_e32 v[32:33], v[116:117]
	v_mov_b64_e32 v[34:35], v[118:119]
	v_mov_b64_e32 v[36:37], v[120:121]
	v_mov_b64_e32 v[38:39], v[122:123]
	v_mov_b64_e32 v[40:41], v[124:125]
	v_mov_b64_e32 v[42:43], v[126:127]
	v_mov_b64_e32 v[44:45], v[128:129]
	v_mov_b64_e32 v[46:47], v[130:131]
	v_mov_b64_e32 v[48:49], v[132:133]
	v_mov_b64_e32 v[50:51], v[134:135]
	v_mov_b64_e32 v[52:53], v[136:137]
	v_mov_b64_e32 v[54:55], v[138:139]
	v_mov_b64_e32 v[56:57], v[140:141]
	v_mov_b64_e32 v[58:59], v[142:143]
	v_mov_b64_e32 v[60:61], v[144:145]
	v_mov_b64_e32 v[62:63], v[146:147]
	v_mov_b64_e32 v[64:65], v[148:149]
	v_mov_b64_e32 v[66:67], v[150:151]
	v_mov_b64_e32 v[72:73], v[156:157]
	v_mov_b64_e32 v[74:75], v[158:159]
	v_mov_b64_e32 v[76:77], v[160:161]
	v_mov_b64_e32 v[78:79], v[162:163]
	v_mov_b64_e32 v[80:81], v[164:165]
	v_mov_b64_e32 v[82:83], v[166:167]
	s_add_i32 s39, s33, 8
	s_add_i32 s33, s33, 16
	v_cmp_gt_u32_e32 vcc, s33, v14
	s_mov_b32 s33, s39
	s_or_b64 s[16:17], vcc, s[16:17]
	v_lshl_add_u64 v[10:11], v[10:11], 0, s[14:15]
	s_mov_b64 s[100:101], exec
	s_andn2_b64 exec, exec, s[16:17]
	s_cbranch_execz .Lp5_noload
	v_add_co_u32_e32 v12, vcc, 0xffdf9000, v10
	global_load_dwordx4 v[100:103], v[10:11], off offset:-4096
	global_load_dwordx4 v[104:107], v[10:11], off
	v_addc_co_u32_e32 v13, vcc, -1, v11, vcc
	v_add_co_u32_e32 v112, vcc, 0xffff9000, v10
	s_nop 0
	s_nop 0
	v_addc_co_u32_e32 v113, vcc, -1, v11, vcc
	v_add_co_u32_e32 v116, vcc, 0xffdfa000, v10
	global_load_dwordx4 v[108:111], v[12:13], off
	s_nop 0
	global_load_dwordx4 v[112:115], v[112:113], off
	v_addc_co_u32_e32 v117, vcc, -1, v11, vcc
	v_add_co_u32_e32 v12, vcc, 0xffffa000, v10
	s_nop 0
	s_nop 0
	v_addc_co_u32_e32 v13, vcc, -1, v11, vcc
	v_add_co_u32_e32 v124, vcc, 0xffdfb000, v10
	global_load_dwordx4 v[116:119], v[116:117], off
	s_nop 0
	global_load_dwordx4 v[120:123], v[12:13], off
	v_addc_co_u32_e32 v125, vcc, -1, v11, vcc
	v_add_co_u32_e32 v12, vcc, 0xffffb000, v10
	s_nop 0
	s_nop 0
	v_addc_co_u32_e32 v13, vcc, -1, v11, vcc
	v_add_co_u32_e32 v132, vcc, 0xffdfc000, v10
	global_load_dwordx4 v[124:127], v[124:125], off
	s_nop 0
	global_load_dwordx4 v[128:131], v[12:13], off
	v_addc_co_u32_e32 v133, vcc, -1, v11, vcc
	v_add_co_u32_e32 v12, vcc, 0xffffc000, v10
	s_nop 0
	s_nop 0
	v_addc_co_u32_e32 v13, vcc, -1, v11, vcc
	v_add_co_u32_e32 v140, vcc, 0xffdfd000, v10
	global_load_dwordx4 v[132:135], v[132:133], off
	s_nop 0
	global_load_dwordx4 v[136:139], v[12:13], off
	v_addc_co_u32_e32 v141, vcc, -1, v11, vcc
	v_add_co_u32_e32 v12, vcc, 0xffffd000, v10
	s_nop 0
	s_nop 0
	v_addc_co_u32_e32 v13, vcc, -1, v11, vcc
	v_add_co_u32_e32 v148, vcc, 0xffdfe000, v10
	global_load_dwordx4 v[140:143], v[140:141], off
	s_nop 0
	global_load_dwordx4 v[144:147], v[12:13], off
	v_addc_co_u32_e32 v149, vcc, -1, v11, vcc
	v_add_co_u32_e32 v12, vcc, 0xffffe000, v10
	s_nop 0
	s_nop 0
	v_addc_co_u32_e32 v13, vcc, -1, v11, vcc
	v_add_co_u32_e32 v68, vcc, 0xffdff000, v10
	global_load_dwordx4 v[148:151], v[148:149], off
	s_nop 0
	global_load_dwordx4 v[156:159], v[12:13], off
	v_addc_co_u32_e32 v69, vcc, -1, v11, vcc
	v_add_co_u32_e32 v12, vcc, 0xffe00000, v10
	global_load_dwordx4 v[160:163], v[68:69], off
	s_nop 0
	v_addc_co_u32_e32 v13, vcc, -1, v11, vcc
	global_load_dwordx4 v[164:167], v[12:13], off
.Lp5_noload:
	s_mov_b64 exec, s[100:101]
	v_mov_b32_e32 v12, s39
	v_pk_fma_f32 v[4:5], v[4:5], v[26:27], v[30:31]
	v_pk_fma_f32 v[2:3], v[2:3], v[24:25], v[28:29]
	v_pk_fma_f32 v[4:5], v[4:5], v[34:35], v[38:39]
	v_pk_fma_f32 v[2:3], v[2:3], v[32:33], v[36:37]
	v_pk_fma_f32 v[4:5], v[4:5], v[42:43], v[46:47]
	v_pk_fma_f32 v[2:3], v[2:3], v[40:41], v[44:45]
	v_pk_fma_f32 v[4:5], v[4:5], v[50:51], v[54:55]
	v_pk_fma_f32 v[2:3], v[2:3], v[48:49], v[52:53]
	v_pk_fma_f32 v[4:5], v[4:5], v[58:59], v[62:63]
	v_pk_fma_f32 v[2:3], v[2:3], v[56:57], v[60:61]
	v_pk_fma_f32 v[4:5], v[4:5], v[66:67], v[74:75]
	v_pk_fma_f32 v[2:3], v[2:3], v[64:65], v[72:73]
	v_pk_fma_f32 v[4:5], v[4:5], v[78:79], v[18:19]
	v_pk_fma_f32 v[2:3], v[2:3], v[76:77], v[16:17]
	v_pk_fma_f32 v[4:5], v[4:5], v[82:83], v[22:23]
	v_pk_fma_f32 v[2:3], v[2:3], v[80:81], v[20:21]
	s_andn2_b64 exec, exec, s[16:17]
	s_cbranch_execnz .LBB0_681
	s_or_b64 exec, exec, s[16:17]
